# attention V-transpose LDS image swizzled by row group (8-way bank conflict on the staging writes removed), readers adjusted
# speedup vs baseline: 1.0179x; 1.0005x over previous
; #define LAS __attribute__((address_space(3)))
; __device__ __forceinline__ void attn_phase(LAS unsigned char* lds, bf16* qkv, const float* qgain, const float* kgain, const float* sink, const float* ropetab, int G, int bid) {
;     ...
;     float mq = 0.f, mk = 0.f;
;     for (int d = 0; d < 64; ++d) { mq = fmaxf(mq, fabsf(qgain[d])); mk = fmaxf(mk, fabsf(kgain[d])); }
;     const float Mshift = 8.0f * mq * mk * LOG2E;
;     __syncthreads();
;     ...
;                 const int key = tid >> 3, c = tid & 7;
;                 *(LAS u32x4*)(Ks + key * 160 + c * 16) = pk0;
;                 *(LAS u32x4*)(Ks + (key + 64) * 160 + c * 16) = pk1;
;                 const int kp = tid >> 3;
; #pragma unroll
;                 for (int w = 0; w < 4; ++w) {
;                     const unsigned lo = (pv0[w] & 0xffffu) | (pv1[w] << 16), hi = (pv0[w] >> 16) | (pv1[w] & 0xffff0000u);
;                     *(LAS unsigned*)(Vt + (c * 8 + 2 * w) * 272 + kp * 4) = lo;
;                     *(LAS unsigned*)(Vt + (c * 8 + 2 * w + 1) * 272 + kp * 4) = hi;
;                 }
.LBB0_557:
	s_add_u32 s4, s6, s0
	s_addc_u32 s5, s7, s1
	global_load_dwordx4 v[6:9], v2, s[4:5] offset:16
	global_load_dwordx4 v[10:13], v2, s[4:5]
	s_add_u32 s4, s13, s0
	s_addc_u32 s5, s14, s1
	global_load_dwordx4 v[14:17], v2, s[4:5]
	global_load_dwordx4 v[18:21], v2, s[4:5] offset:16
	s_add_u32 s0, s0, 32
	s_addc_u32 s1, s1, 0
	s_cmpk_eq_i32 s0, 0x100
	s_waitcnt vmcnt(2)
	v_max3_f32 v1, v1, |v10|, |v11|
	v_max3_f32 v1, v1, |v12|, |v13|
	s_waitcnt vmcnt(1)
	v_max3_f32 v0, v0, |v14|, |v15|
	v_max3_f32 v0, v0, |v16|, |v17|
	v_max3_f32 v1, v1, |v6|, |v7|
	s_waitcnt vmcnt(0)
	v_max3_f32 v0, v0, |v18|, |v19|
	v_max3_f32 v1, v1, |v8|, |v9|
	v_max3_f32 v0, v0, |v20|, |v21|
	s_cbranch_scc0 .LBB0_557
	v_readlane_b32 s0, v254, 0
	v_readlane_b32 s1, v254, 1
	s_andn2_b64 vcc, exec, s[0:1]
	s_waitcnt lgkmcnt(0)
	s_barrier
	s_cbranch_vccnz .LBB0_590
	v_mul_f32_e32 v1, 0x41000000, v1
	v_bfe_u32 v3, v4, 4, 2
	v_mul_f32_e32 v0, v0, v1
	v_lshlrev_b32_e32 v8, 4, v3
	v_mov_b32_e32 v9, v2
	v_mul_f32_e32 v174, 0x3fb8aa3b, v0
	v_lshl_add_u64 v[0:1], s[82:83], 0, v[8:9]
	v_and_b32_e32 v9, 64, v222
	v_xor_b32_e32 v5, 16, v222
	v_add_u32_e32 v9, 64, v9
	v_cmp_lt_i32_e32 vcc, v5, v9
	v_ashrrev_i32_e32 v183, 3, v4
	s_movk_i32 s0, 0xa0
	v_cndmask_b32_e32 v5, v222, v5, vcc
	v_lshlrev_b32_e32 v180, 2, v5
	v_xor_b32_e32 v5, 32, v222
	v_cmp_lt_i32_e32 vcc, v5, v9
	v_mul_lo_u32 v9, v183, s0
	v_readlane_b32 s0, v255, 4
	v_cndmask_b32_e32 v5, v222, v5, vcc
	v_lshlrev_b32_e32 v181, 2, v5
	v_lshlrev_b32_e32 v5, 2, v4
	v_and_b32_e32 v5, 64, v5
	v_add_u32_e32 v182, 0, v5
	v_and_b32_e32 v5, 32, v4
	v_lshlrev_b32_e32 v12, 5, v3
	v_mov_b32_e32 v13, v2
	v_readlane_b32 s1, v255, 5
	v_lshlrev_b32_e32 v6, 3, v3
	v_mov_b32_e32 v7, v2
	v_cmp_eq_u32_e64 s[38:39], 0, v5
	v_and_b32_e32 v5, 7, v4
	v_lshl_add_u64 v[144:145], s[0:1], 0, v[12:13]
	s_movk_i32 s0, 0x880
	v_ashrrev_i32_e32 v175, 7, v4
	v_bfe_u32 v176, v4, 6, 1
	v_and_b32_e32 v177, 15, v4
	v_lshlrev_b32_e32 v4, 3, v5
	v_lshlrev_b32_e32 v10, 4, v5
	v_lshl_add_u64 v[142:143], s[82:83], 0, v[6:7]
	v_mad_u32_u24 v5, v5, s0, 0
	s_movk_i32 s0, 0xffc0
	v_not_b32_e32 v7, 47
	v_lshlrev_b32_e32 v11, 2, v3
	v_mad_i32_i24 v141, v176, s0, -16
	v_mad_i32_i24 v147, v176, s0, v7
	v_mad_i32_i24 v146, v176, s0, v223
	v_mul_u32_u24_e32 v7, 0x110, v177
	s_add_i32 s0, 0, 0x5000
	v_lshlrev_b32_e32 v178, 6, v176
	v_add_u32_e32 v9, 0, v9
	v_lshlrev_b32_e32 v14, 2, v183
	v_sub_u32_e32 v185, v11, v177
	v_lshlrev_b32_e32 v3, 7, v177
	v_mov_b32_e32 v11, v2
	v_add3_u32 v186, v7, v6, s0
	v_mul_u32_u24_e32 v6, 0xa0, v177
	v_or_b32_e32 v179, 0xf000, v178
	v_lshlrev_b32_e32 v184, 1, v183
	v_mul_i32_i24_e32 v140, 0xffffffc0, v176
	v_lshl_add_u64 v[148:149], s[82:83], 0, v[10:11]
	v_add3_u32 v187, v6, v8, 0
	v_lshlrev_b32_e32 v150, 1, v4
	v_add_u32_e32 v188, v9, v10
	v_add_u32_e32 v189, v5, v14
	v_and_b32_e32 v240, 7, v209
	v_lshlrev_b32_e32 v240, 4, v240
	v_xor_b32_e32 v189, v189, v240
	v_bfe_u32 v240, v209, 5, 1
	v_lshlrev_b32_e32 v240, 5, v240
	v_sub_u32_e32 v240, 16, v240
	v_bfe_u32 v241, v209, 3, 1
	v_mul_lo_u32 v240, v240, v241
	v_add_u32_e32 v186, v186, v240
	v_add_u32_e32 v190, v182, v3
	s_mov_b32 s13, s2
	s_branch .LBB0_561

; #define LAS __attribute__((address_space(3)))
; __device__ __forceinline__ void attn_phase(LAS unsigned char* lds, bf16* qkv, const float* qgain, const float* kgain, const float* sink, const float* ropetab, int G, int bid) {
;     ...
;             for (int T = 0; T < 4; ++T) {
;                 bf16x8 kf[2][2];
; #pragma unroll
;                 for (int sub = 0; sub < 2; ++sub)
; #pragma unroll
;                     for (int dh = 0; dh < 2; ++dh) kf[sub][dh] = *(const LAS bf16x8*)(Ks + (T * 32 + sub * 16 + fr) * 160 + dh * 64 + fq * 16);
;                 bf16x8 pb[4];
; #pragma unroll
;                 for (int qi = 0; qi < 4; ++qi) {
;                     f32x4 s0 = (f32x4){0.f, 0.f, 0.f, 0.f}, s1 = (f32x4){0.f, 0.f, 0.f, 0.f};
;                     s0 = __builtin_amdgcn_mfma_f32_16x16x32_bf16(kf[0][0], qf[qi][0], s0, 0, 0, 0);
;                     s0 = __builtin_amdgcn_mfma_f32_16x16x32_bf16(kf[0][1], qf[qi][1], s0, 0, 0, 0);
;                     s1 = __builtin_amdgcn_mfma_f32_16x16x32_bf16(kf[1][0], qf[qi][0], s1, 0, 0, 0);
;                     s1 = __builtin_amdgcn_mfma_f32_16x16x32_bf16(kf[1][1], qf[qi][1], s1, 0, 0, 0);
;                     const int mbase = msg * (T * 32 + fq * 4 - (whalf * 64 + qi * 16 + fr));
;                     float p0[4], p1[4];
; #pragma unroll
;                     for (int j = 0; j < 4; ++j) {
;                         const float e0 = __builtin_amdgcn_exp2f(s0[j] - Mshift), e1 = __builtin_amdgcn_exp2f(s1[j] - Mshift);
;                         p0[j] = (mbase + msg * j >= 0) ? e0 : 0.f;
;                         p1[j] = (mbase + msg * (16 + j) >= 0) ? e1 : 0.f;
;                     }
;                     lsum[qi] += (p0[0] + p0[1]) + (p0[2] + p0[3]) + (p1[0] + p1[1]) + (p1[2] + p1[3]);
;                     u32x4 w; w.x = cvt_pk_bf16(p0[0], p0[1]); w.y = cvt_pk_bf16(p0[2], p0[3]); w.z = cvt_pk_bf16(p1[0], p1[1]); w.w = cvt_pk_bf16(p1[2], p1[3]);
;                     pb[qi] = __builtin_bit_cast(bf16x8, w);
;                 }
; #pragma unroll
;                 for (int dt = 0; dt < 4; ++dt) {
;                     const LAS unsigned char* vp = Vt + (dt * 16 + fr) * 272 + (T * 32 + fq * 4) * 2;
;                     const u32x2 lo = *(const LAS u32x2*)vp, hi = *(const LAS u32x2*)(vp + 32);
.LBB0_587:
	ds_read_b128 v[124:127], v153
	ds_read_b128 v[128:131], v153 offset:64
	ds_read_b128 v[132:135], v153 offset:2560
	ds_read_b128 v[136:139], v153 offset:2624
	v_add_u32_e32 v240, s4, v186
	s_xor_b32 s101, s4, 64
	ds_read2_b64 v[224:227], v240 offset1:4
	v_add_u32_e32 v241, 0x1000, v240
	ds_read2_b64 v[228:231], v241 offset0:36 offset1:32
	v_add_u32_e32 v240, s101, v186
	v_add_u32_e32 v241, 0x2000, v240
	ds_read2_b64 v[232:235], v241 offset0:64 offset1:68
	v_add_u32_e32 v241, 0x3000, v240
	ds_read2_b64 v[236:239], v241 offset0:100 offset1:96
	v_add_u32_e32 v205, v151, v141
	s_waitcnt lgkmcnt(7)
	v_mfma_f32_16x16x32_bf16 v[116:119], v[124:127], v[108:111], 0
	v_add_u32_e32 v206, v151, v140
	v_mov_b32_e32 v201, v205
	v_mov_b32_e32 v197, v206
	s_waitcnt lgkmcnt(5)
	v_mfma_f32_16x16x32_bf16 v[120:123], v[132:135], v[108:111], 0
	v_cmp_lt_i32_e64 s[40:41], -1, v201
	v_cmp_lt_i32_e64 s[0:1], -1, v197
	v_add_u32_e32 v153, 0x1400, v153
	v_mfma_f32_16x16x32_bf16 v[116:119], v[128:131], v[112:115], v[116:119]
	s_waitcnt lgkmcnt(4)
	v_mfma_f32_16x16x32_bf16 v[120:123], v[136:139], v[112:115], v[120:123]
	s_nop 5
	v_sub_f32_e32 v116, v116, v174
	v_exp_f32_e32 v191, v116
	v_sub_f32_e32 v116, v120, v174
	v_exp_f32_e32 v192, v116
	v_sub_f32_e32 v116, v117, v174
	v_exp_f32_e32 v194, v116
	v_sub_f32_e32 v116, v121, v174
	v_exp_f32_e32 v196, v116
	v_sub_f32_e32 v116, v118, v174
	v_exp_f32_e32 v198, v116
	v_sub_f32_e32 v116, v122, v174
	v_exp_f32_e32 v200, v116
	v_sub_f32_e32 v116, v119, v174
	v_exp_f32_e32 v202, v116
	v_sub_f32_e32 v116, v123, v174
	v_exp_f32_e32 v204, v116
	v_mfma_f32_16x16x32_bf16 v[116:119], v[124:127], v[68:71], 0
	v_mfma_f32_16x16x32_bf16 v[120:123], v[132:135], v[68:71], 0
	v_mfma_f32_16x16x32_bf16 v[116:119], v[128:131], v[100:103], v[116:119]
	v_mfma_f32_16x16x32_bf16 v[120:123], v[136:139], v[100:103], v[120:123]
	s_nop 6
	v_sub_f32_e32 v116, v116, v174
	v_sub_f32_e32 v120, v120, v174
	v_exp_f32_e32 v116, v116
	v_exp_f32_e32 v193, v120
	v_sub_f32_e32 v120, v121, v174
	v_sub_f32_e32 v117, v117, v174
	v_exp_f32_e32 v195, v120
	v_sub_f32_e32 v120, v122, v174
	v_exp_f32_e32 v117, v117
	v_exp_f32_e32 v199, v120
	v_sub_f32_e32 v120, v123, v174
	v_exp_f32_e32 v203, v120
	v_add_u32_e32 v120, 16, v206
	v_mov_b32_e32 v120, v120
	v_cndmask_b32_e64 v121, 0, v116, s[40:41]
	v_add_u32_e32 v116, 1, v201
	v_cmp_lt_i32_e32 vcc, -1, v120
	v_cndmask_b32_e64 v120, 0, v191, s[0:1]
	v_cndmask_b32_e64 v123, 0, v193, s[0:1]
	v_cmp_lt_i32_e64 s[0:1], -1, v116
	v_add_u32_e32 v191, 1, v197
	v_add_u32_e32 v116, 17, v206
	v_cndmask_b32_e64 v193, 0, v117, s[0:1]
	v_add_u32_e32 v117, 17, v205
	v_sub_f32_e32 v118, v118, v174
	v_cndmask_b32_e32 v122, 0, v192, vcc
	v_cmp_lt_i32_e32 vcc, -1, v191
	v_mov_b32_e32 v117, v117
	v_mov_b32_e32 v116, v116
	v_exp_f32_e32 v118, v118
	v_cndmask_b32_e32 v192, 0, v194, vcc
	v_cmp_lt_i32_e32 vcc, -1, v116
	v_cmp_lt_i32_e64 s[0:1], -1, v117
	v_add_u32_e32 v116, 2, v206
	v_add_u32_e32 v117, 2, v205
	v_mov_b32_e32 v117, v117
	v_mov_b32_e32 v116, v116
	v_sub_f32_e32 v119, v119, v174
	v_cndmask_b32_e64 v195, 0, v195, s[0:1]
	v_cndmask_b32_e32 v194, 0, v196, vcc
	v_cmp_lt_i32_e32 vcc, -1, v116
	v_cmp_lt_i32_e64 s[0:1], -1, v117
	v_add_u32_e32 v116, 18, v206
	v_add_u32_e32 v117, 18, v205
	v_exp_f32_e32 v119, v119
	v_mov_b32_e32 v117, v117
	v_mov_b32_e32 v116, v116
	v_cndmask_b32_e64 v197, 0, v118, s[0:1]
	v_cndmask_b32_e32 v196, 0, v198, vcc
	v_cmp_lt_i32_e32 vcc, -1, v116
	v_cmp_lt_i32_e64 s[0:1], -1, v117
	v_add_u32_e32 v116, 3, v206
	v_add_u32_e32 v117, 3, v205
	v_mov_b32_e32 v117, v117
	v_mov_b32_e32 v116, v116
	v_cndmask_b32_e64 v199, 0, v199, s[0:1]
	v_cndmask_b32_e32 v198, 0, v200, vcc
	v_cmp_lt_i32_e32 vcc, -1, v116
	v_cmp_lt_i32_e64 s[0:1], -1, v117
	v_add_u32_e32 v116, 19, v206
	v_add_u32_e32 v117, 19, v205
	v_cndmask_b32_e64 v201, 0, v119, s[0:1]
	v_cndmask_b32_e32 v200, 0, v202, vcc
	v_mov_b32_e32 v117, v117
	v_mov_b32_e32 v116, v116
	v_cmp_lt_i32_e32 vcc, -1, v116
	v_cmp_lt_i32_e64 s[0:1], -1, v117
	v_pk_add_f32 v[116:117], v[120:121], v[192:193]
	v_pk_add_f32 v[118:119], v[196:197], v[200:201]
	v_cndmask_b32_e64 v203, 0, v203, s[0:1]
	v_cndmask_b32_e32 v202, 0, v204, vcc
	v_pk_add_f32 v[116:117], v[116:117], v[118:119]
	v_pk_add_f32 v[118:119], v[122:123], v[194:195]
	s_nop 0
	v_pk_add_f32 v[116:117], v[116:117], v[118:119]
	v_pk_add_f32 v[118:119], v[198:199], v[202:203]
	s_nop 0
	v_pk_add_f32 v[204:205], v[118:119], v[116:117]
	v_cvt_pk_bf16_f32 v116, v120, v192
	v_cvt_pk_bf16_f32 v118, v122, v194
	v_cvt_pk_bf16_f32 v120, v121, v193
	v_cvt_pk_bf16_f32 v122, v123, v195
	v_mfma_f32_16x16x32_bf16 v[192:195], v[124:127], v[60:63], 0
	v_cvt_pk_bf16_f32 v117, v196, v200
	v_cvt_pk_bf16_f32 v119, v198, v202
	v_cvt_pk_bf16_f32 v121, v197, v201
	v_mfma_f32_16x16x32_bf16 v[124:127], v[124:127], v[52:55], 0
	v_cvt_pk_bf16_f32 v123, v199, v203
	v_pk_add_f32 v[170:171], v[170:171], v[204:205]
	v_mfma_f32_16x16x32_bf16 v[198:201], v[128:131], v[64:67], v[192:195]
	v_mfma_f32_16x16x32_bf16 v[128:131], v[128:131], v[56:59], v[124:127]
	v_mfma_f32_16x16x32_bf16 v[124:127], v[132:135], v[52:55], 0
	s_nop 5
	v_sub_f32_e32 v191, v198, v174
	v_exp_f32_e32 v198, v191
	v_mfma_f32_16x16x32_bf16 v[192:195], v[132:135], v[60:63], 0
	v_mfma_f32_16x16x32_bf16 v[132:135], v[136:139], v[56:59], v[124:127]
	v_mfma_f32_16x16x32_bf16 v[202:205], v[136:139], v[64:67], v[192:195]
	s_nop 1
	v_sub_f32_e32 v124, v128, v174
	v_exp_f32_e32 v136, v124
	s_nop 2
	v_sub_f32_e32 v124, v132, v174
	v_exp_f32_e32 v132, v124
	v_sub_f32_e32 v124, v129, v174
	v_exp_f32_e32 v129, v124
	v_sub_f32_e32 v124, v133, v174
	v_sub_f32_e32 v191, v202, v174
; #define LAS __attribute__((address_space(3)))
; __device__ __forceinline__ void attn_phase(LAS unsigned char* lds, bf16* qkv, const float* qgain, const float* kgain, const float* sink, const float* ropetab, int G, int bid) {
;     ...
;                     const int mbase = msg * (T * 32 + fq * 4 - (whalf * 64 + qi * 16 + fr));
;                     float p0[4], p1[4];
; #pragma unroll
;                     for (int j = 0; j < 4; ++j) {
;                         const float e0 = __builtin_amdgcn_exp2f(s0[j] - Mshift), e1 = __builtin_amdgcn_exp2f(s1[j] - Mshift);
;                         p0[j] = (mbase + msg * j >= 0) ? e0 : 0.f;
;                         p1[j] = (mbase + msg * (16 + j) >= 0) ? e1 : 0.f;
;                     }
;                     lsum[qi] += (p0[0] + p0[1]) + (p0[2] + p0[3]) + (p1[0] + p1[1]) + (p1[2] + p1[3]);
;                     u32x4 w; w.x = cvt_pk_bf16(p0[0], p0[1]); w.y = cvt_pk_bf16(p0[2], p0[3]); w.z = cvt_pk_bf16(p1[0], p1[1]); w.w = cvt_pk_bf16(p1[2], p1[3]);
;                     pb[qi] = __builtin_bit_cast(bf16x8, w);
;                 }
; #pragma unroll
;                 for (int dt = 0; dt < 4; ++dt) {
;                     const LAS unsigned char* vp = Vt + (dt * 16 + fr) * 272 + (T * 32 + fq * 4) * 2;
;                     const u32x2 lo = *(const LAS u32x2*)vp, hi = *(const LAS u32x2*)(vp + 32);
;                     u32x4 w; w.x = lo[0]; w.y = lo[1]; w.z = hi[0]; w.w = hi[1];
;                     const bf16x8 vf = __builtin_bit_cast(bf16x8, w);
; #pragma unroll
;                     for (int qi = 0; qi < 4; ++qi) o[dt][qi] = __builtin_amdgcn_mfma_f32_16x16x32_bf16(vf, pb[qi], o[dt][qi], 0, 0, 0);
;                 }
	v_exp_f32_e32 v128, v124
	v_sub_f32_e32 v124, v130, v174
	v_exp_f32_e32 v197, v191
	v_sub_f32_e32 v191, v199, v174
	v_exp_f32_e32 v127, v124
	v_sub_f32_e32 v124, v134, v174
	v_exp_f32_e32 v196, v191
	v_sub_f32_e32 v191, v203, v174
	v_exp_f32_e32 v126, v124
	v_sub_f32_e32 v124, v131, v174
	v_add_u32_e32 v199, v147, v151
	v_exp_f32_e32 v195, v191
	v_sub_f32_e32 v191, v200, v174
	v_exp_f32_e32 v125, v124
	v_sub_f32_e32 v124, v135, v174
	v_add_u32_e32 v200, v146, v151
	v_add_u32_e32 v134, 16, v199
	v_mov_b32_e32 v135, v199
	v_add_u32_e32 v133, 16, v200
	v_mov_b32_e32 v137, v200
	v_cmp_lt_i32_e64 s[0:1], -1, v135
	v_mov_b32_e32 v134, v134
	v_cmp_lt_i32_e32 vcc, -1, v137
	v_cndmask_b32_e64 v131, 0, v136, s[0:1]
	v_mov_b32_e32 v133, v133
	v_cmp_lt_i32_e64 s[0:1], -1, v134
	v_add_u32_e32 v134, 1, v135
	v_cndmask_b32_e32 v130, 0, v198, vcc
	v_cmp_lt_i32_e32 vcc, -1, v133
	v_cndmask_b32_e64 v133, 0, v132, s[0:1]
	v_add_u32_e32 v135, 1, v137
	v_cmp_lt_i32_e64 s[0:1], -1, v134
	v_cndmask_b32_e32 v132, 0, v197, vcc
	v_cmp_lt_i32_e32 vcc, -1, v135
	v_cndmask_b32_e64 v135, 0, v129, s[0:1]
	v_add_u32_e32 v129, 17, v200
	v_add_u32_e32 v136, 17, v199
	v_mov_b32_e32 v129, v129
	v_cndmask_b32_e32 v134, 0, v196, vcc
	v_mov_b32_e32 v136, v136
	v_cmp_lt_i32_e32 vcc, -1, v129
	v_add_u32_e32 v129, 2, v199
	v_exp_f32_e32 v194, v191
	v_cmp_lt_i32_e64 s[0:1], -1, v136
	v_mov_b32_e32 v129, v129
	v_sub_f32_e32 v191, v204, v174
	v_cndmask_b32_e64 v137, 0, v128, s[0:1]
	v_add_u32_e32 v128, 2, v200
	v_cmp_lt_i32_e64 s[0:1], -1, v129
	v_add_u32_e32 v138, 18, v199
	v_exp_f32_e32 v193, v191
	v_mov_b32_e32 v128, v128
	v_cndmask_b32_e64 v129, 0, v127, s[0:1]
	v_add_u32_e32 v127, 18, v200
	v_mov_b32_e32 v138, v138
	v_sub_f32_e32 v191, v201, v174
	v_cndmask_b32_e32 v136, 0, v195, vcc
	v_cmp_lt_i32_e32 vcc, -1, v128
	v_mov_b32_e32 v127, v127
	v_cmp_lt_i32_e64 s[0:1], -1, v138
	v_exp_f32_e32 v192, v191
	v_cndmask_b32_e32 v128, 0, v194, vcc
	v_cmp_lt_i32_e32 vcc, -1, v127
	v_cndmask_b32_e64 v139, 0, v126, s[0:1]
	v_add_u32_e32 v126, 3, v200
	v_add_u32_e32 v127, 3, v199
	v_sub_f32_e32 v191, v205, v174
	v_exp_f32_e32 v124, v124
	v_mov_b32_e32 v127, v127
	v_mov_b32_e32 v126, v126
	v_exp_f32_e32 v191, v191
	v_cndmask_b32_e32 v138, 0, v193, vcc
	v_cmp_lt_i32_e32 vcc, -1, v126
	v_cmp_lt_i32_e64 s[0:1], -1, v127
	v_add_u32_e32 v126, 19, v199
	v_mov_b32_e32 v126, v126
	v_cndmask_b32_e64 v193, 0, v125, s[0:1]
	v_add_u32_e32 v125, 19, v200
	v_cndmask_b32_e32 v192, 0, v192, vcc
	v_mov_b32_e32 v125, v125
	v_cmp_lt_i32_e64 s[0:1], -1, v126
	v_cmp_lt_i32_e32 vcc, -1, v125
	v_pk_add_f32 v[126:127], v[128:129], v[192:193]
	v_cndmask_b32_e64 v195, 0, v124, s[0:1]
	v_pk_add_f32 v[124:125], v[130:131], v[134:135]
	v_cndmask_b32_e32 v194, 0, v191, vcc
	v_pk_add_f32 v[124:125], v[124:125], v[126:127]
	v_pk_add_f32 v[126:127], v[132:133], v[136:137]
	v_cvt_pk_bf16_f32 v129, v129, v193
	v_pk_add_f32 v[124:125], v[124:125], v[126:127]
	v_pk_add_f32 v[126:127], v[138:139], v[194:195]
	v_add_u32_e32 v151, 32, v151
	v_pk_add_f32 v[196:197], v[126:127], v[124:125]
	v_cvt_pk_bf16_f32 v126, v132, v136
	v_cvt_pk_bf16_f32 v124, v130, v134
	v_cvt_pk_bf16_f32 v125, v128, v192
	v_cvt_pk_bf16_f32 v128, v131, v135
	v_cvt_pk_bf16_f32 v130, v133, v137
	v_cvt_pk_bf16_f32 v127, v138, v194
	v_cvt_pk_bf16_f32 v131, v139, v195
	s_waitcnt lgkmcnt(0)
	v_mfma_f32_16x16x32_bf16 v[104:107], v[224:227], v[116:119], v[104:107]
	s_add_i32 s4, s4, 64
	v_pk_add_f32 v[160:161], v[160:161], v[196:197]
	s_cmpk_eq_i32 s4, 0x100
	v_mfma_f32_16x16x32_bf16 v[48:51], v[224:227], v[120:123], v[48:51]
	v_mfma_f32_16x16x32_bf16 v[32:35], v[224:227], v[124:127], v[32:35]
	v_mfma_f32_16x16x32_bf16 v[16:19], v[224:227], v[128:131], v[16:19]
	v_mfma_f32_16x16x32_bf16 v[96:99], v[228:231], v[116:119], v[96:99]
	v_mfma_f32_16x16x32_bf16 v[40:43], v[228:231], v[120:123], v[40:43]
	v_mfma_f32_16x16x32_bf16 v[24:27], v[228:231], v[124:127], v[24:27]
	v_mfma_f32_16x16x32_bf16 v[4:7], v[228:231], v[128:131], v[4:7]
	v_mfma_f32_16x16x32_bf16 v[88:91], v[232:235], v[116:119], v[88:91]
	v_mfma_f32_16x16x32_bf16 v[44:47], v[232:235], v[120:123], v[44:47]
	v_mfma_f32_16x16x32_bf16 v[28:31], v[232:235], v[124:127], v[28:31]
	v_mfma_f32_16x16x32_bf16 v[12:15], v[232:235], v[128:131], v[12:15]
	v_mfma_f32_16x16x32_bf16 v[80:83], v[236:239], v[116:119], v[80:83]
	v_mfma_f32_16x16x32_bf16 v[36:39], v[236:239], v[120:123], v[36:39]
	v_mfma_f32_16x16x32_bf16 v[20:23], v[236:239], v[124:127], v[20:23]
	v_mfma_f32_16x16x32_bf16 v[8:11], v[236:239], v[128:131], v[8:11]
	s_cbranch_scc0 .LBB0_587
	s_branch .Latt_exit
; #define LAS __attribute__((address_space(3)))
; __device__ __forceinline__ void attn_phase(LAS unsigned char* lds, bf16* qkv, const float* qgain, const float* kgain, const float* sink, const float* ropetab, int G, int bid) {
;     ...
;             for (int T = 0; T < 4; ++T) {
;                 bf16x8 kf[2][2];
; #pragma unroll
;                 for (int sub = 0; sub < 2; ++sub)
; #pragma unroll
;                     for (int dh = 0; dh < 2; ++dh) kf[sub][dh] = *(const LAS bf16x8*)(Ks + (T * 32 + sub * 16 + fr) * 160 + dh * 64 + fq * 16);
;                 bf16x8 pb[4];
; #pragma unroll
;                 for (int qi = 0; qi < 4; ++qi) {
;                     f32x4 s0 = (f32x4){0.f, 0.f, 0.f, 0.f}, s1 = (f32x4){0.f, 0.f, 0.f, 0.f};
;                     s0 = __builtin_amdgcn_mfma_f32_16x16x32_bf16(kf[0][0], qf[qi][0], s0, 0, 0, 0);
;                     s0 = __builtin_amdgcn_mfma_f32_16x16x32_bf16(kf[0][1], qf[qi][1], s0, 0, 0, 0);
;                     s1 = __builtin_amdgcn_mfma_f32_16x16x32_bf16(kf[1][0], qf[qi][0], s1, 0, 0, 0);
;                     s1 = __builtin_amdgcn_mfma_f32_16x16x32_bf16(kf[1][1], qf[qi][1], s1, 0, 0, 0);
;                     const int mbase = msg * (T * 32 + fq * 4 - (whalf * 64 + qi * 16 + fr));
;                     float p0[4], p1[4];
; #pragma unroll
;                     for (int j = 0; j < 4; ++j) {
;                         const float e0 = __builtin_amdgcn_exp2f(s0[j] - Mshift), e1 = __builtin_amdgcn_exp2f(s1[j] - Mshift);
;                         p0[j] = (mbase + msg * j >= 0) ? e0 : 0.f;
;                         p1[j] = (mbase + msg * (16 + j) >= 0) ? e1 : 0.f;
;                     }
;                     lsum[qi] += (p0[0] + p0[1]) + (p0[2] + p0[3]) + (p1[0] + p1[1]) + (p1[2] + p1[3]);
;                     u32x4 w; w.x = cvt_pk_bf16(p0[0], p0[1]); w.y = cvt_pk_bf16(p0[2], p0[3]); w.z = cvt_pk_bf16(p1[0], p1[1]); w.w = cvt_pk_bf16(p1[2], p1[3]);
;                     pb[qi] = __builtin_bit_cast(bf16x8, w);
;                 }
; #pragma unroll
;                 for (int dt = 0; dt < 4; ++dt) {
;                     const LAS unsigned char* vp = Vt + (dt * 16 + fr) * 272 + (T * 32 + fq * 4) * 2;
;                     const u32x2 lo = *(const LAS u32x2*)vp, hi = *(const LAS u32x2*)(vp + 32);
.LattN_587:
	ds_read_b128 v[124:127], v153
	ds_read_b128 v[128:131], v153 offset:64
	ds_read_b128 v[132:135], v153 offset:2560
	ds_read_b128 v[136:139], v153 offset:2624
	v_add_u32_e32 v240, s4, v186
	s_xor_b32 s101, s4, 64
	ds_read2_b64 v[224:227], v240 offset1:4
	v_add_u32_e32 v241, 0x1000, v240
	ds_read2_b64 v[228:231], v241 offset0:36 offset1:32
	v_add_u32_e32 v240, s101, v186
	v_add_u32_e32 v241, 0x2000, v240
	ds_read2_b64 v[232:235], v241 offset0:64 offset1:68
	v_add_u32_e32 v241, 0x3000, v240
	ds_read2_b64 v[236:239], v241 offset0:100 offset1:96
	v_add_u32_e32 v205, v151, v141
	s_waitcnt lgkmcnt(7)
	v_mfma_f32_16x16x32_bf16 v[116:119], v[124:127], v[108:111], 0
	v_add_u32_e32 v206, v151, v140
	v_mov_b32_e32 v201, v205
	v_mov_b32_e32 v197, v206
	s_waitcnt lgkmcnt(5)
	v_mfma_f32_16x16x32_bf16 v[120:123], v[132:135], v[108:111], 0
	v_cmp_gt_i32_e64 s[40:41], 1, v201
	v_cmp_gt_i32_e64 s[0:1], 1, v197
	v_add_u32_e32 v153, 0x1400, v153
	v_mfma_f32_16x16x32_bf16 v[116:119], v[128:131], v[112:115], v[116:119]
	s_waitcnt lgkmcnt(4)
	v_mfma_f32_16x16x32_bf16 v[120:123], v[136:139], v[112:115], v[120:123]
	s_nop 5
	v_sub_f32_e32 v116, v116, v174
	v_exp_f32_e32 v191, v116
	v_sub_f32_e32 v116, v120, v174
	v_exp_f32_e32 v192, v116
	v_sub_f32_e32 v116, v117, v174
	v_exp_f32_e32 v194, v116
	v_sub_f32_e32 v116, v121, v174
	v_exp_f32_e32 v196, v116
	v_sub_f32_e32 v116, v118, v174
	v_exp_f32_e32 v198, v116
	v_sub_f32_e32 v116, v122, v174
	v_exp_f32_e32 v200, v116
	v_sub_f32_e32 v116, v119, v174
	v_exp_f32_e32 v202, v116
	v_sub_f32_e32 v116, v123, v174
	v_exp_f32_e32 v204, v116
	v_mfma_f32_16x16x32_bf16 v[116:119], v[124:127], v[68:71], 0
	v_mfma_f32_16x16x32_bf16 v[120:123], v[132:135], v[68:71], 0
	v_mfma_f32_16x16x32_bf16 v[116:119], v[128:131], v[100:103], v[116:119]
	v_mfma_f32_16x16x32_bf16 v[120:123], v[136:139], v[100:103], v[120:123]
	s_nop 6
	v_sub_f32_e32 v116, v116, v174
	v_sub_f32_e32 v120, v120, v174
	v_exp_f32_e32 v116, v116
	v_exp_f32_e32 v193, v120
	v_sub_f32_e32 v120, v121, v174
	v_sub_f32_e32 v117, v117, v174
	v_exp_f32_e32 v195, v120
	v_sub_f32_e32 v120, v122, v174
	v_exp_f32_e32 v117, v117
	v_exp_f32_e32 v199, v120
	v_sub_f32_e32 v120, v123, v174
	v_exp_f32_e32 v203, v120
	v_add_u32_e32 v120, 16, v206
	v_mov_b32_e32 v120, v120
	v_cndmask_b32_e64 v121, 0, v116, s[40:41]
	v_add_u32_e32 v116, 1, v201
	v_cmp_gt_i32_e32 vcc, 1, v120
	v_cndmask_b32_e64 v120, 0, v191, s[0:1]
	v_cndmask_b32_e64 v123, 0, v193, s[0:1]
	v_cmp_gt_i32_e64 s[0:1], 1, v116
	v_add_u32_e32 v191, 1, v197
	v_add_u32_e32 v116, 17, v206
	v_cndmask_b32_e64 v193, 0, v117, s[0:1]
	v_add_u32_e32 v117, 17, v205
	v_sub_f32_e32 v118, v118, v174
	v_cndmask_b32_e32 v122, 0, v192, vcc
	v_cmp_gt_i32_e32 vcc, 1, v191
	v_mov_b32_e32 v117, v117
	v_mov_b32_e32 v116, v116
	v_exp_f32_e32 v118, v118
	v_cndmask_b32_e32 v192, 0, v194, vcc
	v_cmp_gt_i32_e32 vcc, 1, v116
	v_cmp_gt_i32_e64 s[0:1], 1, v117
	v_add_u32_e32 v116, 2, v206
	v_add_u32_e32 v117, 2, v205
	v_mov_b32_e32 v117, v117
	v_mov_b32_e32 v116, v116
	v_sub_f32_e32 v119, v119, v174
	v_cndmask_b32_e64 v195, 0, v195, s[0:1]
	v_cndmask_b32_e32 v194, 0, v196, vcc
	v_cmp_gt_i32_e32 vcc, 1, v116
	v_cmp_gt_i32_e64 s[0:1], 1, v117
	v_add_u32_e32 v116, 18, v206
	v_add_u32_e32 v117, 18, v205
	v_exp_f32_e32 v119, v119
	v_mov_b32_e32 v117, v117
	v_mov_b32_e32 v116, v116
	v_cndmask_b32_e64 v197, 0, v118, s[0:1]
	v_cndmask_b32_e32 v196, 0, v198, vcc
	v_cmp_gt_i32_e32 vcc, 1, v116
	v_cmp_gt_i32_e64 s[0:1], 1, v117
	v_add_u32_e32 v116, 3, v206
	v_add_u32_e32 v117, 3, v205
	v_mov_b32_e32 v117, v117
	v_mov_b32_e32 v116, v116
	v_cndmask_b32_e64 v199, 0, v199, s[0:1]
	v_cndmask_b32_e32 v198, 0, v200, vcc
	v_cmp_gt_i32_e32 vcc, 1, v116
	v_cmp_gt_i32_e64 s[0:1], 1, v117
	v_add_u32_e32 v116, 19, v206
	v_add_u32_e32 v117, 19, v205
	v_cndmask_b32_e64 v201, 0, v119, s[0:1]
	v_cndmask_b32_e32 v200, 0, v202, vcc
	v_mov_b32_e32 v117, v117
	v_mov_b32_e32 v116, v116
	v_cmp_gt_i32_e32 vcc, 1, v116
	v_cmp_gt_i32_e64 s[0:1], 1, v117
	v_pk_add_f32 v[116:117], v[120:121], v[192:193]
	v_pk_add_f32 v[118:119], v[196:197], v[200:201]
	v_cndmask_b32_e64 v203, 0, v203, s[0:1]
	v_cndmask_b32_e32 v202, 0, v204, vcc
	v_pk_add_f32 v[116:117], v[116:117], v[118:119]
	v_pk_add_f32 v[118:119], v[122:123], v[194:195]
	s_nop 0
	v_pk_add_f32 v[116:117], v[116:117], v[118:119]
	v_pk_add_f32 v[118:119], v[198:199], v[202:203]
	s_nop 0
	v_pk_add_f32 v[204:205], v[118:119], v[116:117]
	v_cvt_pk_bf16_f32 v116, v120, v192
	v_cvt_pk_bf16_f32 v118, v122, v194
	v_cvt_pk_bf16_f32 v120, v121, v193
	v_cvt_pk_bf16_f32 v122, v123, v195
	v_mfma_f32_16x16x32_bf16 v[192:195], v[124:127], v[60:63], 0
	v_cvt_pk_bf16_f32 v117, v196, v200
	v_cvt_pk_bf16_f32 v119, v198, v202
	v_cvt_pk_bf16_f32 v121, v197, v201
	v_mfma_f32_16x16x32_bf16 v[124:127], v[124:127], v[52:55], 0
	v_cvt_pk_bf16_f32 v123, v199, v203
	v_pk_add_f32 v[170:171], v[170:171], v[204:205]
	v_mfma_f32_16x16x32_bf16 v[198:201], v[128:131], v[64:67], v[192:195]
	v_mfma_f32_16x16x32_bf16 v[128:131], v[128:131], v[56:59], v[124:127]
	v_mfma_f32_16x16x32_bf16 v[124:127], v[132:135], v[52:55], 0
	s_nop 5
	v_sub_f32_e32 v191, v198, v174
	v_exp_f32_e32 v198, v191
	v_mfma_f32_16x16x32_bf16 v[192:195], v[132:135], v[60:63], 0
	v_mfma_f32_16x16x32_bf16 v[132:135], v[136:139], v[56:59], v[124:127]
	v_mfma_f32_16x16x32_bf16 v[202:205], v[136:139], v[64:67], v[192:195]
	s_nop 1
	v_sub_f32_e32 v124, v128, v174
	v_exp_f32_e32 v136, v124
	s_nop 2
	v_sub_f32_e32 v124, v132, v174
	v_exp_f32_e32 v132, v124
	v_sub_f32_e32 v124, v129, v174
	v_exp_f32_e32 v129, v124
	v_sub_f32_e32 v124, v133, v174
	v_sub_f32_e32 v191, v202, v174
	v_exp_f32_e32 v128, v124
; #define LAS __attribute__((address_space(3)))
; __device__ __forceinline__ void attn_phase(LAS unsigned char* lds, bf16* qkv, const float* qgain, const float* kgain, const float* sink, const float* ropetab, int G, int bid) {
;     ...
;                     const int mbase = msg * (T * 32 + fq * 4 - (whalf * 64 + qi * 16 + fr));
;                     float p0[4], p1[4];
; #pragma unroll
;                     for (int j = 0; j < 4; ++j) {
;                         const float e0 = __builtin_amdgcn_exp2f(s0[j] - Mshift), e1 = __builtin_amdgcn_exp2f(s1[j] - Mshift);
;                         p0[j] = (mbase + msg * j >= 0) ? e0 : 0.f;
;                         p1[j] = (mbase + msg * (16 + j) >= 0) ? e1 : 0.f;
;                     }
;                     lsum[qi] += (p0[0] + p0[1]) + (p0[2] + p0[3]) + (p1[0] + p1[1]) + (p1[2] + p1[3]);
;                     u32x4 w; w.x = cvt_pk_bf16(p0[0], p0[1]); w.y = cvt_pk_bf16(p0[2], p0[3]); w.z = cvt_pk_bf16(p1[0], p1[1]); w.w = cvt_pk_bf16(p1[2], p1[3]);
;                     pb[qi] = __builtin_bit_cast(bf16x8, w);
;                 }
; #pragma unroll
;                 for (int dt = 0; dt < 4; ++dt) {
;                     const LAS unsigned char* vp = Vt + (dt * 16 + fr) * 272 + (T * 32 + fq * 4) * 2;
;                     const u32x2 lo = *(const LAS u32x2*)vp, hi = *(const LAS u32x2*)(vp + 32);
;                     u32x4 w; w.x = lo[0]; w.y = lo[1]; w.z = hi[0]; w.w = hi[1];
;                     const bf16x8 vf = __builtin_bit_cast(bf16x8, w);
; #pragma unroll
;                     for (int qi = 0; qi < 4; ++qi) o[dt][qi] = __builtin_amdgcn_mfma_f32_16x16x32_bf16(vf, pb[qi], o[dt][qi], 0, 0, 0);
;                 }
	v_sub_f32_e32 v124, v130, v174
	v_exp_f32_e32 v197, v191
	v_sub_f32_e32 v191, v199, v174
	v_exp_f32_e32 v127, v124
	v_sub_f32_e32 v124, v134, v174
	v_exp_f32_e32 v196, v191
	v_sub_f32_e32 v191, v203, v174
	v_exp_f32_e32 v126, v124
	v_sub_f32_e32 v124, v131, v174
	v_add_u32_e32 v199, v147, v151
	v_exp_f32_e32 v195, v191
	v_sub_f32_e32 v191, v200, v174
	v_exp_f32_e32 v125, v124
	v_sub_f32_e32 v124, v135, v174
	v_add_u32_e32 v200, v146, v151
	v_add_u32_e32 v134, 16, v199
	v_mov_b32_e32 v135, v199
	v_add_u32_e32 v133, 16, v200
	v_mov_b32_e32 v137, v200
	v_cmp_gt_i32_e64 s[0:1], 1, v135
	v_mov_b32_e32 v134, v134
	v_cmp_gt_i32_e32 vcc, 1, v137
	v_cndmask_b32_e64 v131, 0, v136, s[0:1]
	v_mov_b32_e32 v133, v133
	v_cmp_gt_i32_e64 s[0:1], 1, v134
	v_add_u32_e32 v134, 1, v135
	v_cndmask_b32_e32 v130, 0, v198, vcc
	v_cmp_gt_i32_e32 vcc, 1, v133
	v_cndmask_b32_e64 v133, 0, v132, s[0:1]
	v_add_u32_e32 v135, 1, v137
	v_cmp_gt_i32_e64 s[0:1], 1, v134
	v_cndmask_b32_e32 v132, 0, v197, vcc
	v_cmp_gt_i32_e32 vcc, 1, v135
	v_cndmask_b32_e64 v135, 0, v129, s[0:1]
	v_add_u32_e32 v129, 17, v200
	v_add_u32_e32 v136, 17, v199
	v_mov_b32_e32 v129, v129
	v_cndmask_b32_e32 v134, 0, v196, vcc
	v_mov_b32_e32 v136, v136
	v_cmp_gt_i32_e32 vcc, 1, v129
	v_add_u32_e32 v129, 2, v199
	v_exp_f32_e32 v194, v191
	v_cmp_gt_i32_e64 s[0:1], 1, v136
	v_mov_b32_e32 v129, v129
	v_sub_f32_e32 v191, v204, v174
	v_cndmask_b32_e64 v137, 0, v128, s[0:1]
	v_add_u32_e32 v128, 2, v200
	v_cmp_gt_i32_e64 s[0:1], 1, v129
	v_add_u32_e32 v138, 18, v199
	v_exp_f32_e32 v193, v191
	v_mov_b32_e32 v128, v128
	v_cndmask_b32_e64 v129, 0, v127, s[0:1]
	v_add_u32_e32 v127, 18, v200
	v_mov_b32_e32 v138, v138
	v_sub_f32_e32 v191, v201, v174
	v_cndmask_b32_e32 v136, 0, v195, vcc
	v_cmp_gt_i32_e32 vcc, 1, v128
	v_mov_b32_e32 v127, v127
	v_cmp_gt_i32_e64 s[0:1], 1, v138
	v_exp_f32_e32 v192, v191
	v_cndmask_b32_e32 v128, 0, v194, vcc
	v_cmp_gt_i32_e32 vcc, 1, v127
	v_cndmask_b32_e64 v139, 0, v126, s[0:1]
	v_add_u32_e32 v126, 3, v200
	v_add_u32_e32 v127, 3, v199
	v_sub_f32_e32 v191, v205, v174
	v_exp_f32_e32 v124, v124
	v_mov_b32_e32 v127, v127
	v_mov_b32_e32 v126, v126
	v_exp_f32_e32 v191, v191
	v_cndmask_b32_e32 v138, 0, v193, vcc
	v_cmp_gt_i32_e32 vcc, 1, v126
	v_cmp_gt_i32_e64 s[0:1], 1, v127
	v_add_u32_e32 v126, 19, v199
	v_mov_b32_e32 v126, v126
	v_cndmask_b32_e64 v193, 0, v125, s[0:1]
	v_add_u32_e32 v125, 19, v200
	v_cndmask_b32_e32 v192, 0, v192, vcc
	v_mov_b32_e32 v125, v125
	v_cmp_gt_i32_e64 s[0:1], 1, v126
	v_cmp_gt_i32_e32 vcc, 1, v125
	v_pk_add_f32 v[126:127], v[128:129], v[192:193]
	v_cndmask_b32_e64 v195, 0, v124, s[0:1]
	v_pk_add_f32 v[124:125], v[130:131], v[134:135]
	v_cndmask_b32_e32 v194, 0, v191, vcc
	v_pk_add_f32 v[124:125], v[124:125], v[126:127]
	v_pk_add_f32 v[126:127], v[132:133], v[136:137]
	v_cvt_pk_bf16_f32 v129, v129, v193
	v_pk_add_f32 v[124:125], v[124:125], v[126:127]
	v_pk_add_f32 v[126:127], v[138:139], v[194:195]
	v_add_u32_e32 v151, 32, v151
	v_pk_add_f32 v[196:197], v[126:127], v[124:125]
	v_cvt_pk_bf16_f32 v126, v132, v136
	v_cvt_pk_bf16_f32 v124, v130, v134
	v_cvt_pk_bf16_f32 v125, v128, v192
	v_cvt_pk_bf16_f32 v128, v131, v135
	v_cvt_pk_bf16_f32 v130, v133, v137
	v_cvt_pk_bf16_f32 v127, v138, v194
	v_cvt_pk_bf16_f32 v131, v139, v195
	s_waitcnt lgkmcnt(0)
	v_mfma_f32_16x16x32_bf16 v[104:107], v[224:227], v[116:119], v[104:107]
	s_add_i32 s4, s4, 64
	v_pk_add_f32 v[160:161], v[160:161], v[196:197]
	s_cmpk_eq_i32 s4, 0x100
	v_mfma_f32_16x16x32_bf16 v[48:51], v[224:227], v[120:123], v[48:51]
	v_mfma_f32_16x16x32_bf16 v[32:35], v[224:227], v[124:127], v[32:35]
	v_mfma_f32_16x16x32_bf16 v[16:19], v[224:227], v[128:131], v[16:19]
	v_mfma_f32_16x16x32_bf16 v[96:99], v[228:231], v[116:119], v[96:99]
	v_mfma_f32_16x16x32_bf16 v[40:43], v[228:231], v[120:123], v[40:43]
	v_mfma_f32_16x16x32_bf16 v[24:27], v[228:231], v[124:127], v[24:27]
	v_mfma_f32_16x16x32_bf16 v[4:7], v[228:231], v[128:131], v[4:7]
	v_mfma_f32_16x16x32_bf16 v[88:91], v[232:235], v[116:119], v[88:91]
	v_mfma_f32_16x16x32_bf16 v[44:47], v[232:235], v[120:123], v[44:47]
	v_mfma_f32_16x16x32_bf16 v[28:31], v[232:235], v[124:127], v[28:31]
	v_mfma_f32_16x16x32_bf16 v[12:15], v[232:235], v[128:131], v[12:15]
	v_mfma_f32_16x16x32_bf16 v[80:83], v[236:239], v[116:119], v[80:83]
	v_mfma_f32_16x16x32_bf16 v[36:39], v[236:239], v[120:123], v[36:39]
	v_mfma_f32_16x16x32_bf16 v[20:23], v[236:239], v[124:127], v[20:23]
	v_mfma_f32_16x16x32_bf16 v[8:11], v[236:239], v[128:131], v[8:11]
	s_cbranch_scc0 .LattN_587
	s_branch .Latt_exit
; __device__ __forceinline__ void attn_phase(LAS unsigned char* lds, bf16* qkv, const float* qgain, const float* kgain, const float* sink, const float* ropetab, int G, int bid) {
;     ...
;             for (int T = 0; T < 4; ++T) {
;                 bf16x8 kf[2][2];
; #pragma unroll
;                 for (int sub = 0; sub < 2; ++sub)
; #pragma unroll
;                     for (int dh = 0; dh < 2; ++dh) kf[sub][dh] = *(const LAS bf16x8*)(Ks + (T * 32 + sub * 16 + fr) * 160 + dh * 64 + fq * 16);
;                 bf16x8 pb[4];
; #pragma unroll
;                 for (int qi = 0; qi < 4; ++qi) {
;                     f32x4 s0 = (f32x4){0.f, 0.f, 0.f, 0.f}, s1 = (f32x4){0.f, 0.f, 0.f, 0.f};
;                     s0 = __builtin_amdgcn_mfma_f32_16x16x32_bf16(kf[0][0], qf[qi][0], s0, 0, 0, 0);
;                     s0 = __builtin_amdgcn_mfma_f32_16x16x32_bf16(kf[0][1], qf[qi][1], s0, 0, 0, 0);
;                     s1 = __builtin_amdgcn_mfma_f32_16x16x32_bf16(kf[1][0], qf[qi][0], s1, 0, 0, 0);
;                     s1 = __builtin_amdgcn_mfma_f32_16x16x32_bf16(kf[1][1], qf[qi][1], s1, 0, 0, 0);
;                     const int mbase = msg * (T * 32 + fq * 4 - (whalf * 64 + qi * 16 + fr));
;                     float p0[4], p1[4];
; #pragma unroll
;                     for (int j = 0; j < 4; ++j) {
;                         const float e0 = __builtin_amdgcn_exp2f(s0[j] - Mshift), e1 = __builtin_amdgcn_exp2f(s1[j] - Mshift);
;                         p0[j] = (mbase + msg * j >= 0) ? e0 : 0.f;
;                         p1[j] = (mbase + msg * (16 + j) >= 0) ? e1 : 0.f;
;                     }
;                     lsum[qi] += (p0[0] + p0[1]) + (p0[2] + p0[3]) + (p1[0] + p1[1]) + (p1[2] + p1[3]);
;                     u32x4 w; w.x = cvt_pk_bf16(p0[0], p0[1]); w.y = cvt_pk_bf16(p0[2], p0[3]); w.z = cvt_pk_bf16(p1[0], p1[1]); w.w = cvt_pk_bf16(p1[2], p1[3]);
;                     pb[qi] = __builtin_bit_cast(bf16x8, w);
;                 }
; #pragma unroll
;                 for (int dt = 0; dt < 4; ++dt) {
;                     const LAS unsigned char* vp = Vt + (dt * 16 + fr) * 272 + (T * 32 + fq * 4) * 2;
;                     const u32x2 lo = *(const LAS u32x2*)vp, hi = *(const LAS u32x2*)(vp + 32);
;                     u32x4 w; w.x = lo[0]; w.y = lo[1]; w.z = hi[0]; w.w = hi[1];
;                     const bf16x8 vf = __builtin_bit_cast(bf16x8, w);
; #pragma unroll
.LattU_587:
	ds_read_b128 v[124:127], v153
	ds_read_b128 v[128:131], v153 offset:64
	ds_read_b128 v[132:135], v153 offset:2560
	ds_read_b128 v[136:139], v153 offset:2624
	v_add_u32_e32 v240, s4, v186
	s_xor_b32 s101, s4, 64
	ds_read2_b64 v[224:227], v240 offset1:4
	v_add_u32_e32 v241, 0x1000, v240
	ds_read2_b64 v[228:231], v241 offset0:36 offset1:32
	v_add_u32_e32 v240, s101, v186
	v_add_u32_e32 v241, 0x2000, v240
	ds_read2_b64 v[232:235], v241 offset0:64 offset1:68
	v_add_u32_e32 v241, 0x3000, v240
	ds_read2_b64 v[236:239], v241 offset0:100 offset1:96
	s_waitcnt lgkmcnt(7)
	v_mfma_f32_16x16x32_bf16 v[116:119], v[124:127], v[108:111], 0
	s_waitcnt lgkmcnt(5)
	v_mfma_f32_16x16x32_bf16 v[120:123], v[132:135], v[108:111], 0
	v_add_u32_e32 v153, 0x1400, v153
	v_mfma_f32_16x16x32_bf16 v[116:119], v[128:131], v[112:115], v[116:119]
	s_waitcnt lgkmcnt(4)
	v_mfma_f32_16x16x32_bf16 v[120:123], v[136:139], v[112:115], v[120:123]
	s_nop 5
	v_sub_f32_e32 v116, v116, v174
	v_exp_f32_e32 v191, v116
	v_sub_f32_e32 v116, v120, v174
	v_exp_f32_e32 v192, v116
	v_sub_f32_e32 v116, v117, v174
	v_exp_f32_e32 v194, v116
	v_sub_f32_e32 v116, v121, v174
	v_exp_f32_e32 v196, v116
	v_sub_f32_e32 v116, v118, v174
	v_exp_f32_e32 v198, v116
	v_sub_f32_e32 v116, v122, v174
	v_exp_f32_e32 v200, v116
	v_sub_f32_e32 v116, v119, v174
	v_exp_f32_e32 v202, v116
	v_sub_f32_e32 v116, v123, v174
	v_exp_f32_e32 v204, v116
	v_mfma_f32_16x16x32_bf16 v[116:119], v[124:127], v[68:71], 0
	v_mfma_f32_16x16x32_bf16 v[120:123], v[132:135], v[68:71], 0
	v_mfma_f32_16x16x32_bf16 v[116:119], v[128:131], v[100:103], v[116:119]
	v_mfma_f32_16x16x32_bf16 v[120:123], v[136:139], v[100:103], v[120:123]
	s_nop 6
	v_sub_f32_e32 v116, v116, v174
	v_sub_f32_e32 v120, v120, v174
	v_exp_f32_e32 v116, v116
	v_exp_f32_e32 v193, v120
	v_sub_f32_e32 v120, v121, v174
	v_sub_f32_e32 v117, v117, v174
	v_exp_f32_e32 v195, v120
	v_sub_f32_e32 v120, v122, v174
	v_exp_f32_e32 v117, v117
	v_exp_f32_e32 v199, v120
	v_sub_f32_e32 v120, v123, v174
	v_exp_f32_e32 v203, v120
	v_mov_b32_e32 v121, v116
	v_mov_b32_e32 v120, v191
	v_mov_b32_e32 v123, v193
	v_mov_b32_e32 v193, v117
	v_sub_f32_e32 v118, v118, v174
	v_mov_b32_e32 v122, v192
	v_exp_f32_e32 v118, v118
	v_mov_b32_e32 v192, v194
	v_sub_f32_e32 v119, v119, v174
	v_mov_b32_e32 v195, v195
	v_mov_b32_e32 v194, v196
	v_exp_f32_e32 v119, v119
	v_mov_b32_e32 v197, v118
	v_mov_b32_e32 v196, v198
	v_mov_b32_e32 v199, v199
	v_mov_b32_e32 v198, v200
	v_mov_b32_e32 v201, v119
	v_mov_b32_e32 v200, v202
	v_pk_add_f32 v[116:117], v[120:121], v[192:193]
	v_pk_add_f32 v[118:119], v[196:197], v[200:201]
	v_mov_b32_e32 v203, v203
	v_mov_b32_e32 v202, v204
	v_pk_add_f32 v[116:117], v[116:117], v[118:119]
	v_pk_add_f32 v[118:119], v[122:123], v[194:195]
	s_nop 0
	v_pk_add_f32 v[116:117], v[116:117], v[118:119]
	v_pk_add_f32 v[118:119], v[198:199], v[202:203]
	s_nop 0
	v_pk_add_f32 v[204:205], v[118:119], v[116:117]
	v_cvt_pk_bf16_f32 v116, v120, v192
	v_cvt_pk_bf16_f32 v118, v122, v194
	v_cvt_pk_bf16_f32 v120, v121, v193
	v_cvt_pk_bf16_f32 v122, v123, v195
	v_mfma_f32_16x16x32_bf16 v[192:195], v[124:127], v[60:63], 0
	v_cvt_pk_bf16_f32 v117, v196, v200
	v_cvt_pk_bf16_f32 v119, v198, v202
	v_cvt_pk_bf16_f32 v121, v197, v201
	v_mfma_f32_16x16x32_bf16 v[124:127], v[124:127], v[52:55], 0
	v_cvt_pk_bf16_f32 v123, v199, v203
	v_pk_add_f32 v[170:171], v[170:171], v[204:205]
	v_mfma_f32_16x16x32_bf16 v[198:201], v[128:131], v[64:67], v[192:195]
	v_mfma_f32_16x16x32_bf16 v[128:131], v[128:131], v[56:59], v[124:127]
	v_mfma_f32_16x16x32_bf16 v[124:127], v[132:135], v[52:55], 0
	s_nop 5
	v_sub_f32_e32 v191, v198, v174
	v_exp_f32_e32 v198, v191
	v_mfma_f32_16x16x32_bf16 v[192:195], v[132:135], v[60:63], 0
	v_mfma_f32_16x16x32_bf16 v[132:135], v[136:139], v[56:59], v[124:127]
	v_mfma_f32_16x16x32_bf16 v[202:205], v[136:139], v[64:67], v[192:195]
	s_nop 1
	v_sub_f32_e32 v124, v128, v174
	v_exp_f32_e32 v136, v124
	s_nop 2
	v_sub_f32_e32 v124, v132, v174
	v_exp_f32_e32 v132, v124
	v_sub_f32_e32 v124, v129, v174
	v_exp_f32_e32 v129, v124
	v_sub_f32_e32 v124, v133, v174
	v_sub_f32_e32 v191, v202, v174
	v_exp_f32_e32 v128, v124
	v_sub_f32_e32 v124, v130, v174
	v_exp_f32_e32 v197, v191
	v_sub_f32_e32 v191, v199, v174
	v_exp_f32_e32 v127, v124
	v_sub_f32_e32 v124, v134, v174
	v_exp_f32_e32 v196, v191
	v_sub_f32_e32 v191, v203, v174
	v_exp_f32_e32 v126, v124
	v_sub_f32_e32 v124, v131, v174
	v_exp_f32_e32 v195, v191
	v_sub_f32_e32 v191, v200, v174
	v_exp_f32_e32 v125, v124
	v_sub_f32_e32 v124, v135, v174
	v_mov_b32_e32 v131, v136
	v_mov_b32_e32 v130, v198
	v_mov_b32_e32 v133, v132
	v_mov_b32_e32 v132, v197
	v_mov_b32_e32 v135, v129
	v_mov_b32_e32 v134, v196
	v_exp_f32_e32 v194, v191
	v_sub_f32_e32 v191, v204, v174
	v_mov_b32_e32 v137, v128
	v_exp_f32_e32 v193, v191
	v_mov_b32_e32 v129, v127
	v_sub_f32_e32 v191, v201, v174
	v_mov_b32_e32 v136, v195
	v_exp_f32_e32 v192, v191
	v_mov_b32_e32 v128, v194
	v_mov_b32_e32 v139, v126
	v_sub_f32_e32 v191, v205, v174
	v_exp_f32_e32 v124, v124
	v_exp_f32_e32 v191, v191
	v_mov_b32_e32 v138, v193
	v_mov_b32_e32 v193, v125
	v_mov_b32_e32 v192, v192
	v_pk_add_f32 v[126:127], v[128:129], v[192:193]
	v_mov_b32_e32 v195, v124
	v_pk_add_f32 v[124:125], v[130:131], v[134:135]
	v_mov_b32_e32 v194, v191
	v_pk_add_f32 v[124:125], v[124:125], v[126:127]
	v_pk_add_f32 v[126:127], v[132:133], v[136:137]
	v_cvt_pk_bf16_f32 v129, v129, v193
	v_pk_add_f32 v[124:125], v[124:125], v[126:127]
	v_pk_add_f32 v[126:127], v[138:139], v[194:195]
	v_add_u32_e32 v151, 32, v151
	v_pk_add_f32 v[196:197], v[126:127], v[124:125]
	v_cvt_pk_bf16_f32 v126, v132, v136
	v_cvt_pk_bf16_f32 v124, v130, v134
	v_cvt_pk_bf16_f32 v125, v128, v192
	v_cvt_pk_bf16_f32 v128, v131, v135
	v_cvt_pk_bf16_f32 v130, v133, v137
	v_cvt_pk_bf16_f32 v127, v138, v194
	v_cvt_pk_bf16_f32 v131, v139, v195
	s_waitcnt lgkmcnt(0)
; #define LAS __attribute__((address_space(3)))
; __device__ __forceinline__ void attn_phase(LAS unsigned char* lds, bf16* qkv, const float* qgain, const float* kgain, const float* sink, const float* ropetab, int G, int bid) {
;     ...
; #pragma unroll
;                 for (int dt = 0; dt < 4; ++dt) {
;                     const LAS unsigned char* vp = Vt + (dt * 16 + fr) * 272 + (T * 32 + fq * 4) * 2;
;                     const u32x2 lo = *(const LAS u32x2*)vp, hi = *(const LAS u32x2*)(vp + 32);
;                     u32x4 w; w.x = lo[0]; w.y = lo[1]; w.z = hi[0]; w.w = hi[1];
;                     const bf16x8 vf = __builtin_bit_cast(bf16x8, w);
; #pragma unroll
;                     for (int qi = 0; qi < 4; ++qi) o[dt][qi] = __builtin_amdgcn_mfma_f32_16x16x32_bf16(vf, pb[qi], o[dt][qi], 0, 0, 0);
;                 }
;             }
;             sb = nsb;
	v_mfma_f32_16x16x32_bf16 v[104:107], v[224:227], v[116:119], v[104:107]
	s_add_i32 s4, s4, 64
	v_pk_add_f32 v[160:161], v[160:161], v[196:197]
	s_cmpk_eq_i32 s4, 0x100
	v_mfma_f32_16x16x32_bf16 v[48:51], v[224:227], v[120:123], v[48:51]
	v_mfma_f32_16x16x32_bf16 v[32:35], v[224:227], v[124:127], v[32:35]
	v_mfma_f32_16x16x32_bf16 v[16:19], v[224:227], v[128:131], v[16:19]
	v_mfma_f32_16x16x32_bf16 v[96:99], v[228:231], v[116:119], v[96:99]
	v_mfma_f32_16x16x32_bf16 v[40:43], v[228:231], v[120:123], v[40:43]
	v_mfma_f32_16x16x32_bf16 v[24:27], v[228:231], v[124:127], v[24:27]
	v_mfma_f32_16x16x32_bf16 v[4:7], v[228:231], v[128:131], v[4:7]
	v_mfma_f32_16x16x32_bf16 v[88:91], v[232:235], v[116:119], v[88:91]
	v_mfma_f32_16x16x32_bf16 v[44:47], v[232:235], v[120:123], v[44:47]
	v_mfma_f32_16x16x32_bf16 v[28:31], v[232:235], v[124:127], v[28:31]
	v_mfma_f32_16x16x32_bf16 v[12:15], v[232:235], v[128:131], v[12:15]
	v_mfma_f32_16x16x32_bf16 v[80:83], v[236:239], v[116:119], v[80:83]
	v_mfma_f32_16x16x32_bf16 v[36:39], v[236:239], v[120:123], v[36:39]
	v_mfma_f32_16x16x32_bf16 v[20:23], v[236:239], v[124:127], v[20:23]
	v_mfma_f32_16x16x32_bf16 v[8:11], v[236:239], v[128:131], v[8:11]
	s_cbranch_scc0 .LattU_587
	s_branch .Latt_exit

; __global__ void __launch_bounds__(NTHR, 2) fwd_kernel(Args a) {
	.amdhsa_kernel _Z10fwd_kernel4Args
		.amdhsa_group_segment_fixed_size 0
		.amdhsa_private_segment_fixed_size 0
		.amdhsa_kernarg_size 440
		.amdhsa_user_sgpr_count 2
		.amdhsa_user_sgpr_dispatch_ptr 0
		.amdhsa_user_sgpr_queue_ptr 0
		.amdhsa_user_sgpr_kernarg_segment_ptr 1
		.amdhsa_user_sgpr_dispatch_id 0
		.amdhsa_user_sgpr_kernarg_preload_length 0
		.amdhsa_user_sgpr_kernarg_preload_offset 0
		.amdhsa_user_sgpr_private_segment_size 0
		.amdhsa_uses_dynamic_stack 0
		.amdhsa_enable_private_segment 0
		.amdhsa_system_sgpr_workgroup_id_x 1
		.amdhsa_system_sgpr_workgroup_id_y 0
		.amdhsa_system_sgpr_workgroup_id_z 0
		.amdhsa_system_sgpr_workgroup_info 0
		.amdhsa_system_vgpr_workitem_id 2
		.amdhsa_next_free_vgpr 256
		.amdhsa_next_free_sgpr 102
		.amdhsa_accum_offset 256
		.amdhsa_reserve_vcc 1
		.amdhsa_float_round_mode_32 0
		.amdhsa_float_round_mode_16_64 0
		.amdhsa_float_denorm_mode_32 3
		.amdhsa_float_denorm_mode_16_64 3
		.amdhsa_dx10_clamp 1
		.amdhsa_ieee_mode 1
		.amdhsa_fp16_overflow 0
		.amdhsa_tg_split 0
		.amdhsa_exception_fp_ieee_invalid_op 0
		.amdhsa_exception_fp_denorm_src 0
		.amdhsa_exception_fp_ieee_div_zero 0
		.amdhsa_exception_fp_ieee_overflow 0
		.amdhsa_exception_fp_ieee_underflow 0
		.amdhsa_exception_fp_ieee_inexact 0
		.amdhsa_exception_int_div_zero 0
	.end_amdhsa_kernel

; __global__ void __launch_bounds__(NTHR, 2) fwd_kernel(Args a) {
amdhsa.kernels:
  - .agpr_count:     0
    .args:
      - .offset:         0
        .size:           184
        .value_kind:     by_value
      - .offset:         184
        .size:           4
        .value_kind:     hidden_block_count_x
      - .offset:         188
        .size:           4
        .value_kind:     hidden_block_count_y
      - .offset:         192
        .size:           4
        .value_kind:     hidden_block_count_z
      - .offset:         196
        .size:           2
        .value_kind:     hidden_group_size_x
      - .offset:         198
        .size:           2
        .value_kind:     hidden_group_size_y
      - .offset:         200
        .size:           2
        .value_kind:     hidden_group_size_z
      - .offset:         202
        .size:           2
        .value_kind:     hidden_remainder_x
      - .offset:         204
        .size:           2
        .value_kind:     hidden_remainder_y
      - .offset:         206
        .size:           2
        .value_kind:     hidden_remainder_z
      - .offset:         224
        .size:           8
        .value_kind:     hidden_global_offset_x
      - .offset:         232
        .size:           8
        .value_kind:     hidden_global_offset_y
      - .offset:         240
        .size:           8
        .value_kind:     hidden_global_offset_z
      - .offset:         248
        .size:           2
        .value_kind:     hidden_grid_dims
      - .offset:         272
        .size:           8
        .value_kind:     hidden_multigrid_sync_arg
      - .offset:         304
        .size:           4
        .value_kind:     hidden_dynamic_lds_size
    .group_segment_fixed_size: 0
    .kernarg_segment_align: 8
    .kernarg_segment_size: 440
    .language:       OpenCL C
    .language_version:
      - 2
      - 0
    .max_flat_workgroup_size: 512
    .name:           _Z10fwd_kernel4Args
    .private_segment_fixed_size: 0
    .sgpr_count:     108
    .sgpr_spill_count: 249
    .symbol:         _Z10fwd_kernel4Args.kd
    .uniform_work_group_size: 1
    .uses_dynamic_stack: false
    .vgpr_count:     256
    .vgpr_spill_count: 0
    .wavefront_size: 64
